# P9 final candidate merge hand-written: 228 compare/select levels (dominator + occupancy bounds, exact) with v_max/v_min + vcc cndmask instead of the compiler's 800-level cascade
# speedup vs baseline: 1.0089x; 1.0089x over previous
; __device__ __forceinline__ int kmax(int a, int b) { int r; asm("v_max_f32 %0, %1, %2" : "=v"(r) : "v"(a), "v"(b)); return r; }
; __device__ __forceinline__ int kmin(int a, int b) { int r; asm("v_min_f32 %0, %1, %2" : "=v"(r) : "v"(a), "v"(b)); return r; }
; __device__ __forceinline__ int kmed3(int a, int b, int c) { int r; asm("v_med3_f32 %0, %1, %2, %3" : "=v"(r) : "v"(a), "v"(b), "v"(c)); return r; }
; __global__ void __launch_bounds__(NT, 2) mk_fwd(Args args) {
;     ...
;                     for (int j = 0; j < 32; ++j) {
;                         int key = (__float_as_int(scr[lane * 33 + j]) & ~127) | (127 - (nc * 32 + j));
; #pragma unroll
;                         for (int u = 0; u < 16; u += 2) {
;                             const int t0_ = T[u], t1_ = T[u + 1]; T[u] = kmax(t0_, key); T[u + 1] = kmed3(t0_, t1_, key); key = kmin(t1_, key); }
;     ...
;             float tv[16]; int te[16];
; #pragma unroll
;             for (int j = 0; j < 16; ++j) { tv[j] = -3.0e38f; te[j] = 0; }
; #pragma unroll
;             for (int i = 0; i < 16; ++i)
; #pragma unroll
;                 for (int j = 0; j < 16; ++j) if ((i + 1) * (j + 1) <= 16) {
;                     const int m0 = T0[i] & ~127, m1 = T1[j] & ~127;
;                     const float s0 = __int_as_float(m0), s1 = __int_as_float(m1);
;                     float fv = s0 + s1; int pe = ((127 - (T0[i] & 127)) << 7) | (127 - (T1[j] & 127));
; #pragma unroll
;                     for (int u = 0; u < 16; ++u) { const bool c = fv > tv[u]; const float nv = c ? fv : tv[u]; const int ne = c ? pe : te[u]; fv = c ? tv[u] : fv; pe = c ? te[u] : pe; tv[u] = nv; te[u] = ne; }
;                 }
.LBB0_821:
	v_add_u32_e32 v2, s2, v56
	ds_read2_b32 v[0:1], v2 offset1:1
	ds_read2_b32 v[2:3], v2 offset0:2 offset1:3
	s_add_i32 s2, s2, 16
	s_waitcnt lgkmcnt(1)
	v_and_b32_e32 v0, 0xffffff80, v0
	v_and_b32_e32 v1, 0xffffff80, v1
	v_add3_u32 v0, s3, v0, 3
	v_add3_u32 v1, s3, v1, 2
	v_max_f32 v4, v98, v0
	v_med3_f32 v5, v98, v96, v0
	v_min_f32 v0, v96, v0
	s_waitcnt lgkmcnt(0)
	v_and_b32_e32 v2, 0xffffff80, v2
	v_max_f32 v6, v100, v0
	v_med3_f32 v7, v100, v97, v0
	v_min_f32 v0, v97, v0
	v_max_f32 v8, v4, v1
	v_med3_f32 v4, v4, v5, v1
	v_min_f32 v1, v5, v1
	v_and_b32_e32 v3, 0xffffff80, v3
	v_add3_u32 v2, s3, v2, 1
	v_max_f32 v5, v99, v0
	v_med3_f32 v9, v99, v91, v0
	v_min_f32 v0, v91, v0
	v_max_f32 v10, v6, v1
	v_med3_f32 v6, v6, v7, v1
	v_min_f32 v1, v7, v1
	v_add_u32_e32 v3, s3, v3
	v_max_f32 v7, v8, v2
	v_med3_f32 v8, v8, v4, v2
	v_min_f32 v2, v4, v2
	v_max_f32 v4, v92, v0
	v_med3_f32 v11, v92, v94, v0
	v_min_f32 v0, v94, v0
	v_max_f32 v12, v5, v1
	v_med3_f32 v5, v5, v9, v1
	v_min_f32 v1, v9, v1
	s_nop 0
	v_max_f32 v9, v10, v2
	v_med3_f32 v10, v10, v6, v2
	v_min_f32 v2, v6, v2
	v_max_f32 v98, v7, v3
	v_med3_f32 v96, v7, v8, v3
	v_min_f32 v3, v8, v3
	v_max_f32 v6, v93, v0
	v_med3_f32 v7, v93, v95, v0
	v_min_f32 v0, v95, v0
	v_max_f32 v8, v4, v1
	v_med3_f32 v4, v4, v11, v1
	v_min_f32 v1, v11, v1
	s_nop 0
	v_max_f32 v11, v12, v2
	v_med3_f32 v12, v12, v5, v2
	v_min_f32 v2, v5, v2
	v_max_f32 v100, v9, v3
	v_med3_f32 v97, v9, v10, v3
	v_min_f32 v3, v10, v3
	v_max_f32 v5, v90, v0
	v_med3_f32 v9, v90, v89, v0
	v_min_f32 v0, v89, v0
	v_max_f32 v10, v6, v1
	v_med3_f32 v6, v6, v7, v1
	v_min_f32 v1, v7, v1
	s_nop 0
	v_max_f32 v7, v8, v2
	v_med3_f32 v8, v8, v4, v2
	v_min_f32 v2, v4, v2
	v_max_f32 v99, v11, v3
	v_med3_f32 v91, v11, v12, v3
	v_min_f32 v3, v12, v3
	v_max_f32 v4, v88, v0
	v_med3_f32 v11, v88, v87, v0
	v_min_f32 v0, v87, v0
	v_max_f32 v12, v5, v1
	v_med3_f32 v5, v5, v9, v1
	v_min_f32 v1, v9, v1
	s_add_i32 s3, s3, -4
	v_max_f32 v9, v10, v2
	v_med3_f32 v10, v10, v6, v2
	v_min_f32 v2, v6, v2
	v_max_f32 v92, v7, v3
	v_med3_f32 v94, v7, v8, v3
	v_min_f32 v3, v8, v3
	v_max_f32 v6, v86, v0
	v_med3_f32 v0, v86, v84, v0
	v_max_f32 v7, v4, v1
	v_med3_f32 v4, v4, v11, v1
	v_min_f32 v1, v11, v1
	s_cmpk_lg_i32 s2, 0x80
	v_max_f32 v8, v12, v2
	v_med3_f32 v11, v12, v5, v2
	v_min_f32 v2, v5, v2
	v_max_f32 v93, v9, v3
	v_med3_f32 v95, v9, v10, v3
	v_min_f32 v3, v10, v3
	v_max_f32 v5, v6, v1
	v_med3_f32 v0, v6, v0, v1
	s_nop 0
	v_max_f32 v1, v7, v2
	v_med3_f32 v6, v7, v4, v2
	v_min_f32 v2, v4, v2
	v_max_f32 v90, v8, v3
	v_med3_f32 v89, v8, v11, v3
	v_min_f32 v3, v11, v3
	s_nop 0
	v_max_f32 v4, v5, v2
	v_med3_f32 v0, v5, v0, v2
	v_max_f32 v88, v1, v3
	v_med3_f32 v87, v1, v6, v3
	v_min_f32 v1, v6, v3
	s_nop 0
	v_max_f32 v86, v4, v1
	v_med3_f32 v84, v4, v0, v1
	s_cbranch_scc1 .LBB0_821
	s_waitcnt lgkmcnt(0)
	s_add_i32 s0, s0, 1
	s_sub_i32 s1, s1, 32
	s_cmp_lg_u32 s0, 4
	s_cbranch_scc1 .LBB0_820
	v_xor_b32_e32 v101, 0x7f, v85
	v_xor_b32_e32 v38, 0x7f, v98
	v_xor_b32_e32 v102, 0x7f, v83
	v_xor_b32_e32 v39, 0x7f, v96
	v_xor_b32_e32 v103, 0x7f, v82
	v_xor_b32_e32 v40, 0x7f, v100
	v_xor_b32_e32 v104, 0x7f, v81
	v_xor_b32_e32 v41, 0x7f, v97
	v_xor_b32_e32 v105, 0x7f, v80
	v_xor_b32_e32 v42, 0x7f, v99
	v_xor_b32_e32 v106, 0x7f, v79
	v_xor_b32_e32 v43, 0x7f, v91
	v_xor_b32_e32 v107, 0x7f, v78
	v_xor_b32_e32 v44, 0x7f, v92
	v_xor_b32_e32 v108, 0x7f, v77
	v_xor_b32_e32 v45, 0x7f, v94
	v_xor_b32_e32 v109, 0x7f, v76
	v_xor_b32_e32 v46, 0x7f, v93
	v_xor_b32_e32 v110, 0x7f, v75
	v_xor_b32_e32 v47, 0x7f, v95
	v_xor_b32_e32 v111, 0x7f, v74
	v_xor_b32_e32 v48, 0x7f, v90
	v_xor_b32_e32 v112, 0x7f, v73
	v_xor_b32_e32 v49, 0x7f, v89
	v_xor_b32_e32 v113, 0x7f, v72
	v_xor_b32_e32 v50, 0x7f, v88
	v_xor_b32_e32 v114, 0x7f, v71
	v_xor_b32_e32 v51, 0x7f, v87
	v_xor_b32_e32 v115, 0x7f, v70
	v_xor_b32_e32 v52, 0x7f, v86
	v_xor_b32_e32 v116, 0x7f, v69
	v_xor_b32_e32 v53, 0x7f, v84
	v_and_b32_e32 v101, 0x7f, v101
	v_and_b32_e32 v38, 0x7f, v38
	v_and_b32_e32 v102, 0x7f, v102
	v_and_b32_e32 v39, 0x7f, v39
	v_and_b32_e32 v103, 0x7f, v103
	v_and_b32_e32 v40, 0x7f, v40
	v_and_b32_e32 v104, 0x7f, v104
	v_and_b32_e32 v41, 0x7f, v41
	v_and_b32_e32 v105, 0x7f, v105
	v_and_b32_e32 v42, 0x7f, v42
	v_and_b32_e32 v106, 0x7f, v106
	v_and_b32_e32 v43, 0x7f, v43
	v_and_b32_e32 v107, 0x7f, v107
	v_and_b32_e32 v44, 0x7f, v44
	v_and_b32_e32 v108, 0x7f, v108
	v_and_b32_e32 v45, 0x7f, v45
	v_and_b32_e32 v109, 0x7f, v109
	v_and_b32_e32 v46, 0x7f, v46
	v_and_b32_e32 v110, 0x7f, v110
	v_and_b32_e32 v47, 0x7f, v47
	v_and_b32_e32 v111, 0x7f, v111
	v_and_b32_e32 v48, 0x7f, v48
	v_and_b32_e32 v112, 0x7f, v112
	v_and_b32_e32 v49, 0x7f, v49
	v_and_b32_e32 v113, 0x7f, v113
	v_and_b32_e32 v50, 0x7f, v50
	v_and_b32_e32 v114, 0x7f, v114
	v_and_b32_e32 v51, 0x7f, v51
	v_and_b32_e32 v115, 0x7f, v115
	v_and_b32_e32 v52, 0x7f, v52
	v_and_b32_e32 v116, 0x7f, v116
	v_and_b32_e32 v53, 0x7f, v53
	v_and_b32_e32 v85, 0xffffff80, v85
	v_and_b32_e32 v98, 0xffffff80, v98
	v_and_b32_e32 v83, 0xffffff80, v83
	v_and_b32_e32 v96, 0xffffff80, v96
	v_and_b32_e32 v82, 0xffffff80, v82
	v_and_b32_e32 v100, 0xffffff80, v100
	v_and_b32_e32 v81, 0xffffff80, v81
	v_and_b32_e32 v97, 0xffffff80, v97
	v_and_b32_e32 v80, 0xffffff80, v80
	v_and_b32_e32 v99, 0xffffff80, v99
	v_and_b32_e32 v79, 0xffffff80, v79
	v_and_b32_e32 v91, 0xffffff80, v91
	v_and_b32_e32 v78, 0xffffff80, v78
	v_and_b32_e32 v92, 0xffffff80, v92
	v_and_b32_e32 v77, 0xffffff80, v77
	v_and_b32_e32 v94, 0xffffff80, v94
	v_and_b32_e32 v76, 0xffffff80, v76
	v_and_b32_e32 v93, 0xffffff80, v93
	v_and_b32_e32 v75, 0xffffff80, v75
	v_and_b32_e32 v95, 0xffffff80, v95
	v_and_b32_e32 v74, 0xffffff80, v74
; __global__ void __launch_bounds__(NT, 2) mk_fwd(Args args) {
;     ...
;             float tv[16]; int te[16];
; #pragma unroll
;             for (int j = 0; j < 16; ++j) { tv[j] = -3.0e38f; te[j] = 0; }
; #pragma unroll
;             for (int i = 0; i < 16; ++i)
; #pragma unroll
;                 for (int j = 0; j < 16; ++j) if ((i + 1) * (j + 1) <= 16) {
;                     const int m0 = T0[i] & ~127, m1 = T1[j] & ~127;
;                     const float s0 = __int_as_float(m0), s1 = __int_as_float(m1);
;                     float fv = s0 + s1; int pe = ((127 - (T0[i] & 127)) << 7) | (127 - (T1[j] & 127));
; #pragma unroll
;                     for (int u = 0; u < 16; ++u) { const bool c = fv > tv[u]; const float nv = c ? fv : tv[u]; const int ne = c ? pe : te[u]; fv = c ? tv[u] : fv; pe = c ? te[u] : pe; tv[u] = nv; te[u] = ne; }
;                 }
	v_and_b32_e32 v90, 0xffffff80, v90
	v_and_b32_e32 v73, 0xffffff80, v73
	v_and_b32_e32 v89, 0xffffff80, v89
	v_and_b32_e32 v72, 0xffffff80, v72
	v_and_b32_e32 v88, 0xffffff80, v88
	v_and_b32_e32 v71, 0xffffff80, v71
	v_and_b32_e32 v87, 0xffffff80, v87
	v_and_b32_e32 v70, 0xffffff80, v70
	v_and_b32_e32 v86, 0xffffff80, v86
	v_and_b32_e32 v69, 0xffffff80, v69
	v_and_b32_e32 v84, 0xffffff80, v84
	v_add_f32_e32 v16, v85, v98
	v_lshl_or_b32 v0, v101, 7, v38
	v_add_f32_e32 v17, v85, v96
	v_lshl_or_b32 v1, v101, 7, v39
	v_add_f32_e32 v18, v85, v100
	v_lshl_or_b32 v2, v101, 7, v40
	v_add_f32_e32 v19, v85, v97
	v_lshl_or_b32 v3, v101, 7, v41
	v_add_f32_e32 v20, v85, v99
	v_lshl_or_b32 v4, v101, 7, v42
	v_add_f32_e32 v21, v85, v91
	v_lshl_or_b32 v5, v101, 7, v43
	v_add_f32_e32 v22, v85, v92
	v_lshl_or_b32 v6, v101, 7, v44
	v_add_f32_e32 v23, v85, v94
	v_lshl_or_b32 v7, v101, 7, v45
	v_add_f32_e32 v24, v85, v93
	v_lshl_or_b32 v8, v101, 7, v46
	v_add_f32_e32 v25, v85, v95
	v_lshl_or_b32 v9, v101, 7, v47
	v_add_f32_e32 v26, v85, v90
	v_lshl_or_b32 v10, v101, 7, v48
	v_add_f32_e32 v27, v85, v89
	v_lshl_or_b32 v11, v101, 7, v49
	v_add_f32_e32 v28, v85, v88
	v_lshl_or_b32 v12, v101, 7, v50
	v_add_f32_e32 v29, v85, v87
	v_lshl_or_b32 v13, v101, 7, v51
	v_add_f32_e32 v30, v85, v86
	v_lshl_or_b32 v14, v101, 7, v52
	v_add_f32_e32 v31, v85, v84
	v_lshl_or_b32 v15, v101, 7, v53
	v_add_f32_e32 v117, v83, v98
	v_lshl_or_b32 v118, v102, 7, v38
	v_cmp_gt_f32_e32 vcc, v117, v17
	v_min_f32_e32 v119, v117, v17
	v_max_f32_e32 v17, v117, v17
	v_cndmask_b32_e32 v120, v118, v1, vcc
	v_cndmask_b32_e32 v1, v1, v118, vcc
	v_cmp_gt_f32_e32 vcc, v119, v18
	v_min_f32_e32 v117, v119, v18
	v_max_f32_e32 v18, v119, v18
	v_cndmask_b32_e32 v118, v120, v2, vcc
	v_cndmask_b32_e32 v2, v2, v120, vcc
	v_cmp_gt_f32_e32 vcc, v117, v19
	v_min_f32_e32 v119, v117, v19
	v_max_f32_e32 v19, v117, v19
	v_cndmask_b32_e32 v120, v118, v3, vcc
	v_cndmask_b32_e32 v3, v3, v118, vcc
	v_cmp_gt_f32_e32 vcc, v119, v20
	v_min_f32_e32 v117, v119, v20
	v_max_f32_e32 v20, v119, v20
	v_cndmask_b32_e32 v118, v120, v4, vcc
	v_cndmask_b32_e32 v4, v4, v120, vcc
	v_cmp_gt_f32_e32 vcc, v117, v21
	v_min_f32_e32 v119, v117, v21
	v_max_f32_e32 v21, v117, v21
	v_cndmask_b32_e32 v120, v118, v5, vcc
	v_cndmask_b32_e32 v5, v5, v118, vcc
	v_cmp_gt_f32_e32 vcc, v119, v22
	v_min_f32_e32 v117, v119, v22
	v_max_f32_e32 v22, v119, v22
	v_cndmask_b32_e32 v118, v120, v6, vcc
	v_cndmask_b32_e32 v6, v6, v120, vcc
	v_cmp_gt_f32_e32 vcc, v117, v23
	v_min_f32_e32 v119, v117, v23
	v_max_f32_e32 v23, v117, v23
	v_cndmask_b32_e32 v120, v118, v7, vcc
	v_cndmask_b32_e32 v7, v7, v118, vcc
	v_cmp_gt_f32_e32 vcc, v119, v24
	v_min_f32_e32 v117, v119, v24
	v_max_f32_e32 v24, v119, v24
	v_cndmask_b32_e32 v118, v120, v8, vcc
	v_cndmask_b32_e32 v8, v8, v120, vcc
	v_cmp_gt_f32_e32 vcc, v117, v25
	v_min_f32_e32 v119, v117, v25
	v_max_f32_e32 v25, v117, v25
	v_cndmask_b32_e32 v120, v118, v9, vcc
	v_cndmask_b32_e32 v9, v9, v118, vcc
	v_cmp_gt_f32_e32 vcc, v119, v26
	v_min_f32_e32 v117, v119, v26
	v_max_f32_e32 v26, v119, v26
	v_cndmask_b32_e32 v118, v120, v10, vcc
	v_cndmask_b32_e32 v10, v10, v120, vcc
	v_cmp_gt_f32_e32 vcc, v117, v27
	v_min_f32_e32 v119, v117, v27
	v_max_f32_e32 v27, v117, v27
	v_cndmask_b32_e32 v120, v118, v11, vcc
	v_cndmask_b32_e32 v11, v11, v118, vcc
	v_cmp_gt_f32_e32 vcc, v119, v28
	v_min_f32_e32 v117, v119, v28
	v_max_f32_e32 v28, v119, v28
	v_cndmask_b32_e32 v118, v120, v12, vcc
	v_cndmask_b32_e32 v12, v12, v120, vcc
	v_cmp_gt_f32_e32 vcc, v117, v29
	v_min_f32_e32 v119, v117, v29
	v_max_f32_e32 v29, v117, v29
	v_cndmask_b32_e32 v120, v118, v13, vcc
	v_cndmask_b32_e32 v13, v13, v118, vcc
	v_cmp_gt_f32_e32 vcc, v119, v30
	v_min_f32_e32 v117, v119, v30
	v_max_f32_e32 v30, v119, v30
	v_cndmask_b32_e32 v118, v120, v14, vcc
	v_cndmask_b32_e32 v14, v14, v120, vcc
	v_cmp_gt_f32_e32 vcc, v117, v31
	v_min_f32_e32 v119, v117, v31
	v_max_f32_e32 v31, v117, v31
	v_cndmask_b32_e32 v120, v118, v15, vcc
	v_cndmask_b32_e32 v15, v15, v118, vcc
	v_add_f32_e32 v119, v83, v96
	v_lshl_or_b32 v120, v102, 7, v39
	v_cmp_gt_f32_e32 vcc, v119, v19
	v_min_f32_e32 v117, v119, v19
	v_max_f32_e32 v19, v119, v19
	v_cndmask_b32_e32 v118, v120, v3, vcc
	v_cndmask_b32_e32 v3, v3, v120, vcc
	v_cmp_gt_f32_e32 vcc, v117, v20
	v_min_f32_e32 v119, v117, v20
	v_max_f32_e32 v20, v117, v20
	v_cndmask_b32_e32 v120, v118, v4, vcc
	v_cndmask_b32_e32 v4, v4, v118, vcc
	v_cmp_gt_f32_e32 vcc, v119, v21
	v_min_f32_e32 v117, v119, v21
	v_max_f32_e32 v21, v119, v21
	v_cndmask_b32_e32 v118, v120, v5, vcc
	v_cndmask_b32_e32 v5, v5, v120, vcc
	v_cmp_gt_f32_e32 vcc, v117, v22
	v_min_f32_e32 v119, v117, v22
	v_max_f32_e32 v22, v117, v22
	v_cndmask_b32_e32 v120, v118, v6, vcc
	v_cndmask_b32_e32 v6, v6, v118, vcc
	v_cmp_gt_f32_e32 vcc, v119, v23
	v_min_f32_e32 v117, v119, v23
	v_max_f32_e32 v23, v119, v23
	v_cndmask_b32_e32 v118, v120, v7, vcc
	v_cndmask_b32_e32 v7, v7, v120, vcc
	v_cmp_gt_f32_e32 vcc, v117, v24
	v_min_f32_e32 v119, v117, v24
	v_max_f32_e32 v24, v117, v24
	v_cndmask_b32_e32 v120, v118, v8, vcc
	v_cndmask_b32_e32 v8, v8, v118, vcc
	v_cmp_gt_f32_e32 vcc, v119, v25
	v_min_f32_e32 v117, v119, v25
	v_max_f32_e32 v25, v119, v25
	v_cndmask_b32_e32 v118, v120, v9, vcc
	v_cndmask_b32_e32 v9, v9, v120, vcc
	v_cmp_gt_f32_e32 vcc, v117, v26
	v_min_f32_e32 v119, v117, v26
	v_max_f32_e32 v26, v117, v26
	v_cndmask_b32_e32 v120, v118, v10, vcc
	v_cndmask_b32_e32 v10, v10, v118, vcc
	v_cmp_gt_f32_e32 vcc, v119, v27
	v_min_f32_e32 v117, v119, v27
	v_max_f32_e32 v27, v119, v27
	v_cndmask_b32_e32 v118, v120, v11, vcc
	v_cndmask_b32_e32 v11, v11, v120, vcc
	v_cmp_gt_f32_e32 vcc, v117, v28
; __global__ void __launch_bounds__(NT, 2) mk_fwd(Args args) {
;     ...
;             for (int i = 0; i < 16; ++i)
; #pragma unroll
;                 for (int j = 0; j < 16; ++j) if ((i + 1) * (j + 1) <= 16) {
;                     const int m0 = T0[i] & ~127, m1 = T1[j] & ~127;
;                     const float s0 = __int_as_float(m0), s1 = __int_as_float(m1);
;                     float fv = s0 + s1; int pe = ((127 - (T0[i] & 127)) << 7) | (127 - (T1[j] & 127));
; #pragma unroll
;                     for (int u = 0; u < 16; ++u) { const bool c = fv > tv[u]; const float nv = c ? fv : tv[u]; const int ne = c ? pe : te[u]; fv = c ? tv[u] : fv; pe = c ? te[u] : pe; tv[u] = nv; te[u] = ne; }
;                 }
	v_min_f32_e32 v119, v117, v28
	v_max_f32_e32 v28, v117, v28
	v_cndmask_b32_e32 v120, v118, v12, vcc
	v_cndmask_b32_e32 v12, v12, v118, vcc
	v_cmp_gt_f32_e32 vcc, v119, v29
	v_min_f32_e32 v117, v119, v29
	v_max_f32_e32 v29, v119, v29
	v_cndmask_b32_e32 v118, v120, v13, vcc
	v_cndmask_b32_e32 v13, v13, v120, vcc
	v_cmp_gt_f32_e32 vcc, v117, v30
	v_min_f32_e32 v119, v117, v30
	v_max_f32_e32 v30, v117, v30
	v_cndmask_b32_e32 v120, v118, v14, vcc
	v_cndmask_b32_e32 v14, v14, v118, vcc
	v_cmp_gt_f32_e32 vcc, v119, v31
	v_min_f32_e32 v117, v119, v31
	v_max_f32_e32 v31, v119, v31
	v_cndmask_b32_e32 v118, v120, v15, vcc
	v_cndmask_b32_e32 v15, v15, v120, vcc
	v_add_f32_e32 v117, v83, v100
	v_lshl_or_b32 v118, v102, 7, v40
	v_cmp_gt_f32_e32 vcc, v117, v21
	v_min_f32_e32 v119, v117, v21
	v_max_f32_e32 v21, v117, v21
	v_cndmask_b32_e32 v120, v118, v5, vcc
	v_cndmask_b32_e32 v5, v5, v118, vcc
	v_cmp_gt_f32_e32 vcc, v119, v22
	v_min_f32_e32 v117, v119, v22
	v_max_f32_e32 v22, v119, v22
	v_cndmask_b32_e32 v118, v120, v6, vcc
	v_cndmask_b32_e32 v6, v6, v120, vcc
	v_cmp_gt_f32_e32 vcc, v117, v23
	v_min_f32_e32 v119, v117, v23
	v_max_f32_e32 v23, v117, v23
	v_cndmask_b32_e32 v120, v118, v7, vcc
	v_cndmask_b32_e32 v7, v7, v118, vcc
	v_cmp_gt_f32_e32 vcc, v119, v24
	v_min_f32_e32 v117, v119, v24
	v_max_f32_e32 v24, v119, v24
	v_cndmask_b32_e32 v118, v120, v8, vcc
	v_cndmask_b32_e32 v8, v8, v120, vcc
	v_cmp_gt_f32_e32 vcc, v117, v25
	v_min_f32_e32 v119, v117, v25
	v_max_f32_e32 v25, v117, v25
	v_cndmask_b32_e32 v120, v118, v9, vcc
	v_cndmask_b32_e32 v9, v9, v118, vcc
	v_cmp_gt_f32_e32 vcc, v119, v26
	v_min_f32_e32 v117, v119, v26
	v_max_f32_e32 v26, v119, v26
	v_cndmask_b32_e32 v118, v120, v10, vcc
	v_cndmask_b32_e32 v10, v10, v120, vcc
	v_cmp_gt_f32_e32 vcc, v117, v27
	v_min_f32_e32 v119, v117, v27
	v_max_f32_e32 v27, v117, v27
	v_cndmask_b32_e32 v120, v118, v11, vcc
	v_cndmask_b32_e32 v11, v11, v118, vcc
	v_cmp_gt_f32_e32 vcc, v119, v28
	v_min_f32_e32 v117, v119, v28
	v_max_f32_e32 v28, v119, v28
	v_cndmask_b32_e32 v118, v120, v12, vcc
	v_cndmask_b32_e32 v12, v12, v120, vcc
	v_cmp_gt_f32_e32 vcc, v117, v29
	v_min_f32_e32 v119, v117, v29
	v_max_f32_e32 v29, v117, v29
	v_cndmask_b32_e32 v120, v118, v13, vcc
	v_cndmask_b32_e32 v13, v13, v118, vcc
	v_cmp_gt_f32_e32 vcc, v119, v30
	v_min_f32_e32 v117, v119, v30
	v_max_f32_e32 v30, v119, v30
	v_cndmask_b32_e32 v118, v120, v14, vcc
	v_cndmask_b32_e32 v14, v14, v120, vcc
	v_cmp_gt_f32_e32 vcc, v117, v31
	v_min_f32_e32 v119, v117, v31
	v_max_f32_e32 v31, v117, v31
	v_cndmask_b32_e32 v120, v118, v15, vcc
	v_cndmask_b32_e32 v15, v15, v118, vcc
	v_add_f32_e32 v119, v83, v97
	v_lshl_or_b32 v120, v102, 7, v41
	v_cmp_gt_f32_e32 vcc, v119, v23
	v_min_f32_e32 v117, v119, v23
	v_max_f32_e32 v23, v119, v23
	v_cndmask_b32_e32 v118, v120, v7, vcc
	v_cndmask_b32_e32 v7, v7, v120, vcc
	v_cmp_gt_f32_e32 vcc, v117, v24
	v_min_f32_e32 v119, v117, v24
	v_max_f32_e32 v24, v117, v24
	v_cndmask_b32_e32 v120, v118, v8, vcc
	v_cndmask_b32_e32 v8, v8, v118, vcc
	v_cmp_gt_f32_e32 vcc, v119, v25
	v_min_f32_e32 v117, v119, v25
	v_max_f32_e32 v25, v119, v25
	v_cndmask_b32_e32 v118, v120, v9, vcc
	v_cndmask_b32_e32 v9, v9, v120, vcc
	v_cmp_gt_f32_e32 vcc, v117, v26
	v_min_f32_e32 v119, v117, v26
	v_max_f32_e32 v26, v117, v26
	v_cndmask_b32_e32 v120, v118, v10, vcc
	v_cndmask_b32_e32 v10, v10, v118, vcc
	v_cmp_gt_f32_e32 vcc, v119, v27
	v_min_f32_e32 v117, v119, v27
	v_max_f32_e32 v27, v119, v27
	v_cndmask_b32_e32 v118, v120, v11, vcc
	v_cndmask_b32_e32 v11, v11, v120, vcc
	v_cmp_gt_f32_e32 vcc, v117, v28
	v_min_f32_e32 v119, v117, v28
	v_max_f32_e32 v28, v117, v28
	v_cndmask_b32_e32 v120, v118, v12, vcc
	v_cndmask_b32_e32 v12, v12, v118, vcc
	v_cmp_gt_f32_e32 vcc, v119, v29
	v_min_f32_e32 v117, v119, v29
	v_max_f32_e32 v29, v119, v29
	v_cndmask_b32_e32 v118, v120, v13, vcc
	v_cndmask_b32_e32 v13, v13, v120, vcc
	v_cmp_gt_f32_e32 vcc, v117, v30
	v_min_f32_e32 v119, v117, v30
	v_max_f32_e32 v30, v117, v30
	v_cndmask_b32_e32 v120, v118, v14, vcc
	v_cndmask_b32_e32 v14, v14, v118, vcc
	v_cmp_gt_f32_e32 vcc, v119, v31
	v_min_f32_e32 v117, v119, v31
	v_max_f32_e32 v31, v119, v31
	v_cndmask_b32_e32 v118, v120, v15, vcc
	v_cndmask_b32_e32 v15, v15, v120, vcc
	v_add_f32_e32 v117, v83, v99
	v_lshl_or_b32 v118, v102, 7, v42
	v_cmp_gt_f32_e32 vcc, v117, v25
	v_min_f32_e32 v119, v117, v25
	v_max_f32_e32 v25, v117, v25
	v_cndmask_b32_e32 v120, v118, v9, vcc
	v_cndmask_b32_e32 v9, v9, v118, vcc
	v_cmp_gt_f32_e32 vcc, v119, v26
	v_min_f32_e32 v117, v119, v26
	v_max_f32_e32 v26, v119, v26
	v_cndmask_b32_e32 v118, v120, v10, vcc
	v_cndmask_b32_e32 v10, v10, v120, vcc
	v_cmp_gt_f32_e32 vcc, v117, v27
	v_min_f32_e32 v119, v117, v27
	v_max_f32_e32 v27, v117, v27
	v_cndmask_b32_e32 v120, v118, v11, vcc
	v_cndmask_b32_e32 v11, v11, v118, vcc
	v_cmp_gt_f32_e32 vcc, v119, v28
	v_min_f32_e32 v117, v119, v28
	v_max_f32_e32 v28, v119, v28
	v_cndmask_b32_e32 v118, v120, v12, vcc
	v_cndmask_b32_e32 v12, v12, v120, vcc
	v_cmp_gt_f32_e32 vcc, v117, v29
	v_min_f32_e32 v119, v117, v29
	v_max_f32_e32 v29, v117, v29
	v_cndmask_b32_e32 v120, v118, v13, vcc
	v_cndmask_b32_e32 v13, v13, v118, vcc
	v_cmp_gt_f32_e32 vcc, v119, v30
	v_min_f32_e32 v117, v119, v30
	v_max_f32_e32 v30, v119, v30
	v_cndmask_b32_e32 v118, v120, v14, vcc
	v_cndmask_b32_e32 v14, v14, v120, vcc
	v_cmp_gt_f32_e32 vcc, v117, v31
	v_min_f32_e32 v119, v117, v31
	v_max_f32_e32 v31, v117, v31
	v_cndmask_b32_e32 v120, v118, v15, vcc
	v_cndmask_b32_e32 v15, v15, v118, vcc
	v_add_f32_e32 v119, v83, v91
	v_lshl_or_b32 v120, v102, 7, v43
	v_cmp_gt_f32_e32 vcc, v119, v27
	v_min_f32_e32 v117, v119, v27
	v_max_f32_e32 v27, v119, v27
; __global__ void __launch_bounds__(NT, 2) mk_fwd(Args args) {
;     ...
;             for (int i = 0; i < 16; ++i)
; #pragma unroll
;                 for (int j = 0; j < 16; ++j) if ((i + 1) * (j + 1) <= 16) {
;                     const int m0 = T0[i] & ~127, m1 = T1[j] & ~127;
;                     const float s0 = __int_as_float(m0), s1 = __int_as_float(m1);
;                     float fv = s0 + s1; int pe = ((127 - (T0[i] & 127)) << 7) | (127 - (T1[j] & 127));
; #pragma unroll
;                     for (int u = 0; u < 16; ++u) { const bool c = fv > tv[u]; const float nv = c ? fv : tv[u]; const int ne = c ? pe : te[u]; fv = c ? tv[u] : fv; pe = c ? te[u] : pe; tv[u] = nv; te[u] = ne; }
;                 }
	v_cndmask_b32_e32 v118, v120, v11, vcc
	v_cndmask_b32_e32 v11, v11, v120, vcc
	v_cmp_gt_f32_e32 vcc, v117, v28
	v_min_f32_e32 v119, v117, v28
	v_max_f32_e32 v28, v117, v28
	v_cndmask_b32_e32 v120, v118, v12, vcc
	v_cndmask_b32_e32 v12, v12, v118, vcc
	v_cmp_gt_f32_e32 vcc, v119, v29
	v_min_f32_e32 v117, v119, v29
	v_max_f32_e32 v29, v119, v29
	v_cndmask_b32_e32 v118, v120, v13, vcc
	v_cndmask_b32_e32 v13, v13, v120, vcc
	v_cmp_gt_f32_e32 vcc, v117, v30
	v_min_f32_e32 v119, v117, v30
	v_max_f32_e32 v30, v117, v30
	v_cndmask_b32_e32 v120, v118, v14, vcc
	v_cndmask_b32_e32 v14, v14, v118, vcc
	v_cmp_gt_f32_e32 vcc, v119, v31
	v_min_f32_e32 v117, v119, v31
	v_max_f32_e32 v31, v119, v31
	v_cndmask_b32_e32 v118, v120, v15, vcc
	v_cndmask_b32_e32 v15, v15, v120, vcc
	v_add_f32_e32 v117, v83, v92
	v_lshl_or_b32 v118, v102, 7, v44
	v_cmp_gt_f32_e32 vcc, v117, v29
	v_min_f32_e32 v119, v117, v29
	v_max_f32_e32 v29, v117, v29
	v_cndmask_b32_e32 v120, v118, v13, vcc
	v_cndmask_b32_e32 v13, v13, v118, vcc
	v_cmp_gt_f32_e32 vcc, v119, v30
	v_min_f32_e32 v117, v119, v30
	v_max_f32_e32 v30, v119, v30
	v_cndmask_b32_e32 v118, v120, v14, vcc
	v_cndmask_b32_e32 v14, v14, v120, vcc
	v_cmp_gt_f32_e32 vcc, v117, v31
	v_min_f32_e32 v119, v117, v31
	v_max_f32_e32 v31, v117, v31
	v_cndmask_b32_e32 v120, v118, v15, vcc
	v_cndmask_b32_e32 v15, v15, v118, vcc
	v_add_f32_e32 v119, v83, v94
	v_lshl_or_b32 v120, v102, 7, v45
	v_cmp_gt_f32_e32 vcc, v119, v31
	v_min_f32_e32 v117, v119, v31
	v_max_f32_e32 v31, v119, v31
	v_cndmask_b32_e32 v118, v120, v15, vcc
	v_cndmask_b32_e32 v15, v15, v120, vcc
	v_add_f32_e32 v117, v82, v98
	v_lshl_or_b32 v118, v103, 7, v38
	v_cmp_gt_f32_e32 vcc, v117, v18
	v_min_f32_e32 v119, v117, v18
	v_max_f32_e32 v18, v117, v18
	v_cndmask_b32_e32 v120, v118, v2, vcc
	v_cndmask_b32_e32 v2, v2, v118, vcc
	v_cmp_gt_f32_e32 vcc, v119, v19
	v_min_f32_e32 v117, v119, v19
	v_max_f32_e32 v19, v119, v19
	v_cndmask_b32_e32 v118, v120, v3, vcc
	v_cndmask_b32_e32 v3, v3, v120, vcc
	v_cmp_gt_f32_e32 vcc, v117, v20
	v_min_f32_e32 v119, v117, v20
	v_max_f32_e32 v20, v117, v20
	v_cndmask_b32_e32 v120, v118, v4, vcc
	v_cndmask_b32_e32 v4, v4, v118, vcc
	v_cmp_gt_f32_e32 vcc, v119, v21
	v_min_f32_e32 v117, v119, v21
	v_max_f32_e32 v21, v119, v21
	v_cndmask_b32_e32 v118, v120, v5, vcc
	v_cndmask_b32_e32 v5, v5, v120, vcc
	v_cmp_gt_f32_e32 vcc, v117, v22
	v_min_f32_e32 v119, v117, v22
	v_max_f32_e32 v22, v117, v22
	v_cndmask_b32_e32 v120, v118, v6, vcc
	v_cndmask_b32_e32 v6, v6, v118, vcc
	v_cmp_gt_f32_e32 vcc, v119, v23
	v_min_f32_e32 v117, v119, v23
	v_max_f32_e32 v23, v119, v23
	v_cndmask_b32_e32 v118, v120, v7, vcc
	v_cndmask_b32_e32 v7, v7, v120, vcc
	v_cmp_gt_f32_e32 vcc, v117, v24
	v_min_f32_e32 v119, v117, v24
	v_max_f32_e32 v24, v117, v24
	v_cndmask_b32_e32 v120, v118, v8, vcc
	v_cndmask_b32_e32 v8, v8, v118, vcc
	v_cmp_gt_f32_e32 vcc, v119, v25
	v_min_f32_e32 v117, v119, v25
	v_max_f32_e32 v25, v119, v25
	v_cndmask_b32_e32 v118, v120, v9, vcc
	v_cndmask_b32_e32 v9, v9, v120, vcc
	v_cmp_gt_f32_e32 vcc, v117, v26
	v_min_f32_e32 v119, v117, v26
	v_max_f32_e32 v26, v117, v26
	v_cndmask_b32_e32 v120, v118, v10, vcc
	v_cndmask_b32_e32 v10, v10, v118, vcc
	v_cmp_gt_f32_e32 vcc, v119, v27
	v_min_f32_e32 v117, v119, v27
	v_max_f32_e32 v27, v119, v27
	v_cndmask_b32_e32 v118, v120, v11, vcc
	v_cndmask_b32_e32 v11, v11, v120, vcc
	v_cmp_gt_f32_e32 vcc, v117, v28
	v_min_f32_e32 v119, v117, v28
	v_max_f32_e32 v28, v117, v28
	v_cndmask_b32_e32 v120, v118, v12, vcc
	v_cndmask_b32_e32 v12, v12, v118, vcc
	v_cmp_gt_f32_e32 vcc, v119, v29
	v_min_f32_e32 v117, v119, v29
	v_max_f32_e32 v29, v119, v29
	v_cndmask_b32_e32 v118, v120, v13, vcc
	v_cndmask_b32_e32 v13, v13, v120, vcc
	v_cmp_gt_f32_e32 vcc, v117, v30
	v_min_f32_e32 v119, v117, v30
	v_max_f32_e32 v30, v117, v30
	v_cndmask_b32_e32 v120, v118, v14, vcc
	v_cndmask_b32_e32 v14, v14, v118, vcc
	v_cmp_gt_f32_e32 vcc, v119, v31
	v_min_f32_e32 v117, v119, v31
	v_max_f32_e32 v31, v119, v31
	v_cndmask_b32_e32 v118, v120, v15, vcc
	v_cndmask_b32_e32 v15, v15, v120, vcc
	v_add_f32_e32 v117, v82, v96
	v_lshl_or_b32 v118, v103, 7, v39
	v_cmp_gt_f32_e32 vcc, v117, v21
	v_min_f32_e32 v119, v117, v21
	v_max_f32_e32 v21, v117, v21
	v_cndmask_b32_e32 v120, v118, v5, vcc
	v_cndmask_b32_e32 v5, v5, v118, vcc
	v_cmp_gt_f32_e32 vcc, v119, v22
	v_min_f32_e32 v117, v119, v22
	v_max_f32_e32 v22, v119, v22
	v_cndmask_b32_e32 v118, v120, v6, vcc
	v_cndmask_b32_e32 v6, v6, v120, vcc
	v_cmp_gt_f32_e32 vcc, v117, v23
	v_min_f32_e32 v119, v117, v23
	v_max_f32_e32 v23, v117, v23
	v_cndmask_b32_e32 v120, v118, v7, vcc
	v_cndmask_b32_e32 v7, v7, v118, vcc
	v_cmp_gt_f32_e32 vcc, v119, v24
	v_min_f32_e32 v117, v119, v24
	v_max_f32_e32 v24, v119, v24
	v_cndmask_b32_e32 v118, v120, v8, vcc
	v_cndmask_b32_e32 v8, v8, v120, vcc
	v_cmp_gt_f32_e32 vcc, v117, v25
	v_min_f32_e32 v119, v117, v25
	v_max_f32_e32 v25, v117, v25
	v_cndmask_b32_e32 v120, v118, v9, vcc
	v_cndmask_b32_e32 v9, v9, v118, vcc
	v_cmp_gt_f32_e32 vcc, v119, v26
	v_min_f32_e32 v117, v119, v26
	v_max_f32_e32 v26, v119, v26
	v_cndmask_b32_e32 v118, v120, v10, vcc
	v_cndmask_b32_e32 v10, v10, v120, vcc
	v_cmp_gt_f32_e32 vcc, v117, v27
	v_min_f32_e32 v119, v117, v27
	v_max_f32_e32 v27, v117, v27
	v_cndmask_b32_e32 v120, v118, v11, vcc
	v_cndmask_b32_e32 v11, v11, v118, vcc
	v_cmp_gt_f32_e32 vcc, v119, v28
	v_min_f32_e32 v117, v119, v28
	v_max_f32_e32 v28, v119, v28
	v_cndmask_b32_e32 v118, v120, v12, vcc
	v_cndmask_b32_e32 v12, v12, v120, vcc
	v_cmp_gt_f32_e32 vcc, v117, v29
	v_min_f32_e32 v119, v117, v29
	v_max_f32_e32 v29, v117, v29
	v_cndmask_b32_e32 v120, v118, v13, vcc
	v_cndmask_b32_e32 v13, v13, v118, vcc
; __global__ void __launch_bounds__(NT, 2) mk_fwd(Args args) {
;     ...
;             for (int i = 0; i < 16; ++i)
; #pragma unroll
;                 for (int j = 0; j < 16; ++j) if ((i + 1) * (j + 1) <= 16) {
;                     const int m0 = T0[i] & ~127, m1 = T1[j] & ~127;
;                     const float s0 = __int_as_float(m0), s1 = __int_as_float(m1);
;                     float fv = s0 + s1; int pe = ((127 - (T0[i] & 127)) << 7) | (127 - (T1[j] & 127));
; #pragma unroll
;                     for (int u = 0; u < 16; ++u) { const bool c = fv > tv[u]; const float nv = c ? fv : tv[u]; const int ne = c ? pe : te[u]; fv = c ? tv[u] : fv; pe = c ? te[u] : pe; tv[u] = nv; te[u] = ne; }
;                 }
	v_cmp_gt_f32_e32 vcc, v119, v30
	v_min_f32_e32 v117, v119, v30
	v_max_f32_e32 v30, v119, v30
	v_cndmask_b32_e32 v118, v120, v14, vcc
	v_cndmask_b32_e32 v14, v14, v120, vcc
	v_cmp_gt_f32_e32 vcc, v117, v31
	v_min_f32_e32 v119, v117, v31
	v_max_f32_e32 v31, v117, v31
	v_cndmask_b32_e32 v120, v118, v15, vcc
	v_cndmask_b32_e32 v15, v15, v118, vcc
	v_add_f32_e32 v119, v82, v100
	v_lshl_or_b32 v120, v103, 7, v40
	v_cmp_gt_f32_e32 vcc, v119, v24
	v_min_f32_e32 v117, v119, v24
	v_max_f32_e32 v24, v119, v24
	v_cndmask_b32_e32 v118, v120, v8, vcc
	v_cndmask_b32_e32 v8, v8, v120, vcc
	v_cmp_gt_f32_e32 vcc, v117, v25
	v_min_f32_e32 v119, v117, v25
	v_max_f32_e32 v25, v117, v25
	v_cndmask_b32_e32 v120, v118, v9, vcc
	v_cndmask_b32_e32 v9, v9, v118, vcc
	v_cmp_gt_f32_e32 vcc, v119, v26
	v_min_f32_e32 v117, v119, v26
	v_max_f32_e32 v26, v119, v26
	v_cndmask_b32_e32 v118, v120, v10, vcc
	v_cndmask_b32_e32 v10, v10, v120, vcc
	v_cmp_gt_f32_e32 vcc, v117, v27
	v_min_f32_e32 v119, v117, v27
	v_max_f32_e32 v27, v117, v27
	v_cndmask_b32_e32 v120, v118, v11, vcc
	v_cndmask_b32_e32 v11, v11, v118, vcc
	v_cmp_gt_f32_e32 vcc, v119, v28
	v_min_f32_e32 v117, v119, v28
	v_max_f32_e32 v28, v119, v28
	v_cndmask_b32_e32 v118, v120, v12, vcc
	v_cndmask_b32_e32 v12, v12, v120, vcc
	v_cmp_gt_f32_e32 vcc, v117, v29
	v_min_f32_e32 v119, v117, v29
	v_max_f32_e32 v29, v117, v29
	v_cndmask_b32_e32 v120, v118, v13, vcc
	v_cndmask_b32_e32 v13, v13, v118, vcc
	v_cmp_gt_f32_e32 vcc, v119, v30
	v_min_f32_e32 v117, v119, v30
	v_max_f32_e32 v30, v119, v30
	v_cndmask_b32_e32 v118, v120, v14, vcc
	v_cndmask_b32_e32 v14, v14, v120, vcc
	v_cmp_gt_f32_e32 vcc, v117, v31
	v_min_f32_e32 v119, v117, v31
	v_max_f32_e32 v31, v117, v31
	v_cndmask_b32_e32 v120, v118, v15, vcc
	v_cndmask_b32_e32 v15, v15, v118, vcc
	v_add_f32_e32 v119, v82, v97
	v_lshl_or_b32 v120, v103, 7, v41
	v_cmp_gt_f32_e32 vcc, v119, v27
	v_min_f32_e32 v117, v119, v27
	v_max_f32_e32 v27, v119, v27
	v_cndmask_b32_e32 v118, v120, v11, vcc
	v_cndmask_b32_e32 v11, v11, v120, vcc
	v_cmp_gt_f32_e32 vcc, v117, v28
	v_min_f32_e32 v119, v117, v28
	v_max_f32_e32 v28, v117, v28
	v_cndmask_b32_e32 v120, v118, v12, vcc
	v_cndmask_b32_e32 v12, v12, v118, vcc
	v_cmp_gt_f32_e32 vcc, v119, v29
	v_min_f32_e32 v117, v119, v29
	v_max_f32_e32 v29, v119, v29
	v_cndmask_b32_e32 v118, v120, v13, vcc
	v_cndmask_b32_e32 v13, v13, v120, vcc
	v_cmp_gt_f32_e32 vcc, v117, v30
	v_min_f32_e32 v119, v117, v30
	v_max_f32_e32 v30, v117, v30
	v_cndmask_b32_e32 v120, v118, v14, vcc
	v_cndmask_b32_e32 v14, v14, v118, vcc
	v_cmp_gt_f32_e32 vcc, v119, v31
	v_min_f32_e32 v117, v119, v31
	v_max_f32_e32 v31, v119, v31
	v_cndmask_b32_e32 v118, v120, v15, vcc
	v_cndmask_b32_e32 v15, v15, v120, vcc
	v_add_f32_e32 v117, v82, v99
	v_lshl_or_b32 v118, v103, 7, v42
	v_cmp_gt_f32_e32 vcc, v117, v30
	v_min_f32_e32 v119, v117, v30
	v_max_f32_e32 v30, v117, v30
	v_cndmask_b32_e32 v120, v118, v14, vcc
	v_cndmask_b32_e32 v14, v14, v118, vcc
	v_cmp_gt_f32_e32 vcc, v119, v31
	v_min_f32_e32 v117, v119, v31
	v_max_f32_e32 v31, v119, v31
	v_cndmask_b32_e32 v118, v120, v15, vcc
	v_cndmask_b32_e32 v15, v15, v120, vcc
	v_add_f32_e32 v117, v81, v98
	v_lshl_or_b32 v118, v104, 7, v38
	v_cmp_gt_f32_e32 vcc, v117, v19
	v_min_f32_e32 v119, v117, v19
	v_max_f32_e32 v19, v117, v19
	v_cndmask_b32_e32 v120, v118, v3, vcc
	v_cndmask_b32_e32 v3, v3, v118, vcc
	v_cmp_gt_f32_e32 vcc, v119, v20
	v_min_f32_e32 v117, v119, v20
	v_max_f32_e32 v20, v119, v20
	v_cndmask_b32_e32 v118, v120, v4, vcc
	v_cndmask_b32_e32 v4, v4, v120, vcc
	v_cmp_gt_f32_e32 vcc, v117, v21
	v_min_f32_e32 v119, v117, v21
	v_max_f32_e32 v21, v117, v21
	v_cndmask_b32_e32 v120, v118, v5, vcc
	v_cndmask_b32_e32 v5, v5, v118, vcc
	v_cmp_gt_f32_e32 vcc, v119, v22
	v_min_f32_e32 v117, v119, v22
	v_max_f32_e32 v22, v119, v22
	v_cndmask_b32_e32 v118, v120, v6, vcc
	v_cndmask_b32_e32 v6, v6, v120, vcc
	v_cmp_gt_f32_e32 vcc, v117, v23
	v_min_f32_e32 v119, v117, v23
	v_max_f32_e32 v23, v117, v23
	v_cndmask_b32_e32 v120, v118, v7, vcc
	v_cndmask_b32_e32 v7, v7, v118, vcc
	v_cmp_gt_f32_e32 vcc, v119, v24
	v_min_f32_e32 v117, v119, v24
	v_max_f32_e32 v24, v119, v24
	v_cndmask_b32_e32 v118, v120, v8, vcc
	v_cndmask_b32_e32 v8, v8, v120, vcc
	v_cmp_gt_f32_e32 vcc, v117, v25
	v_min_f32_e32 v119, v117, v25
	v_max_f32_e32 v25, v117, v25
	v_cndmask_b32_e32 v120, v118, v9, vcc
	v_cndmask_b32_e32 v9, v9, v118, vcc
	v_cmp_gt_f32_e32 vcc, v119, v26
	v_min_f32_e32 v117, v119, v26
	v_max_f32_e32 v26, v119, v26
	v_cndmask_b32_e32 v118, v120, v10, vcc
	v_cndmask_b32_e32 v10, v10, v120, vcc
	v_cmp_gt_f32_e32 vcc, v117, v27
	v_min_f32_e32 v119, v117, v27
	v_max_f32_e32 v27, v117, v27
	v_cndmask_b32_e32 v120, v118, v11, vcc
	v_cndmask_b32_e32 v11, v11, v118, vcc
	v_cmp_gt_f32_e32 vcc, v119, v28
	v_min_f32_e32 v117, v119, v28
	v_max_f32_e32 v28, v119, v28
	v_cndmask_b32_e32 v118, v120, v12, vcc
	v_cndmask_b32_e32 v12, v12, v120, vcc
	v_cmp_gt_f32_e32 vcc, v117, v29
	v_min_f32_e32 v119, v117, v29
	v_max_f32_e32 v29, v117, v29
	v_cndmask_b32_e32 v120, v118, v13, vcc
	v_cndmask_b32_e32 v13, v13, v118, vcc
	v_cmp_gt_f32_e32 vcc, v119, v30
	v_min_f32_e32 v117, v119, v30
	v_max_f32_e32 v30, v119, v30
	v_cndmask_b32_e32 v118, v120, v14, vcc
	v_cndmask_b32_e32 v14, v14, v120, vcc
	v_cmp_gt_f32_e32 vcc, v117, v31
	v_min_f32_e32 v119, v117, v31
	v_max_f32_e32 v31, v117, v31
	v_cndmask_b32_e32 v120, v118, v15, vcc
	v_cndmask_b32_e32 v15, v15, v118, vcc
	v_add_f32_e32 v119, v81, v96
	v_lshl_or_b32 v120, v104, 7, v39
	v_cmp_gt_f32_e32 vcc, v119, v23
	v_min_f32_e32 v117, v119, v23
	v_max_f32_e32 v23, v119, v23
	v_cndmask_b32_e32 v118, v120, v7, vcc
	v_cndmask_b32_e32 v7, v7, v120, vcc
; __global__ void __launch_bounds__(NT, 2) mk_fwd(Args args) {
;     ...
;             for (int i = 0; i < 16; ++i)
; #pragma unroll
;                 for (int j = 0; j < 16; ++j) if ((i + 1) * (j + 1) <= 16) {
;                     const int m0 = T0[i] & ~127, m1 = T1[j] & ~127;
;                     const float s0 = __int_as_float(m0), s1 = __int_as_float(m1);
;                     float fv = s0 + s1; int pe = ((127 - (T0[i] & 127)) << 7) | (127 - (T1[j] & 127));
; #pragma unroll
;                     for (int u = 0; u < 16; ++u) { const bool c = fv > tv[u]; const float nv = c ? fv : tv[u]; const int ne = c ? pe : te[u]; fv = c ? tv[u] : fv; pe = c ? te[u] : pe; tv[u] = nv; te[u] = ne; }
;                 }
	v_cmp_gt_f32_e32 vcc, v117, v24
	v_min_f32_e32 v119, v117, v24
	v_max_f32_e32 v24, v117, v24
	v_cndmask_b32_e32 v120, v118, v8, vcc
	v_cndmask_b32_e32 v8, v8, v118, vcc
	v_cmp_gt_f32_e32 vcc, v119, v25
	v_min_f32_e32 v117, v119, v25
	v_max_f32_e32 v25, v119, v25
	v_cndmask_b32_e32 v118, v120, v9, vcc
	v_cndmask_b32_e32 v9, v9, v120, vcc
	v_cmp_gt_f32_e32 vcc, v117, v26
	v_min_f32_e32 v119, v117, v26
	v_max_f32_e32 v26, v117, v26
	v_cndmask_b32_e32 v120, v118, v10, vcc
	v_cndmask_b32_e32 v10, v10, v118, vcc
	v_cmp_gt_f32_e32 vcc, v119, v27
	v_min_f32_e32 v117, v119, v27
	v_max_f32_e32 v27, v119, v27
	v_cndmask_b32_e32 v118, v120, v11, vcc
	v_cndmask_b32_e32 v11, v11, v120, vcc
	v_cmp_gt_f32_e32 vcc, v117, v28
	v_min_f32_e32 v119, v117, v28
	v_max_f32_e32 v28, v117, v28
	v_cndmask_b32_e32 v120, v118, v12, vcc
	v_cndmask_b32_e32 v12, v12, v118, vcc
	v_cmp_gt_f32_e32 vcc, v119, v29
	v_min_f32_e32 v117, v119, v29
	v_max_f32_e32 v29, v119, v29
	v_cndmask_b32_e32 v118, v120, v13, vcc
	v_cndmask_b32_e32 v13, v13, v120, vcc
	v_cmp_gt_f32_e32 vcc, v117, v30
	v_min_f32_e32 v119, v117, v30
	v_max_f32_e32 v30, v117, v30
	v_cndmask_b32_e32 v120, v118, v14, vcc
	v_cndmask_b32_e32 v14, v14, v118, vcc
	v_cmp_gt_f32_e32 vcc, v119, v31
	v_min_f32_e32 v117, v119, v31
	v_max_f32_e32 v31, v119, v31
	v_cndmask_b32_e32 v118, v120, v15, vcc
	v_cndmask_b32_e32 v15, v15, v120, vcc
	v_add_f32_e32 v117, v81, v100
	v_lshl_or_b32 v118, v104, 7, v40
	v_cmp_gt_f32_e32 vcc, v117, v27
	v_min_f32_e32 v119, v117, v27
	v_max_f32_e32 v27, v117, v27
	v_cndmask_b32_e32 v120, v118, v11, vcc
	v_cndmask_b32_e32 v11, v11, v118, vcc
	v_cmp_gt_f32_e32 vcc, v119, v28
	v_min_f32_e32 v117, v119, v28
	v_max_f32_e32 v28, v119, v28
	v_cndmask_b32_e32 v118, v120, v12, vcc
	v_cndmask_b32_e32 v12, v12, v120, vcc
	v_cmp_gt_f32_e32 vcc, v117, v29
	v_min_f32_e32 v119, v117, v29
	v_max_f32_e32 v29, v117, v29
	v_cndmask_b32_e32 v120, v118, v13, vcc
	v_cndmask_b32_e32 v13, v13, v118, vcc
	v_cmp_gt_f32_e32 vcc, v119, v30
	v_min_f32_e32 v117, v119, v30
	v_max_f32_e32 v30, v119, v30
	v_cndmask_b32_e32 v118, v120, v14, vcc
	v_cndmask_b32_e32 v14, v14, v120, vcc
	v_cmp_gt_f32_e32 vcc, v117, v31
	v_min_f32_e32 v119, v117, v31
	v_max_f32_e32 v31, v117, v31
	v_cndmask_b32_e32 v120, v118, v15, vcc
	v_cndmask_b32_e32 v15, v15, v118, vcc
	v_add_f32_e32 v119, v81, v97
	v_lshl_or_b32 v120, v104, 7, v41
	v_cmp_gt_f32_e32 vcc, v119, v31
	v_min_f32_e32 v117, v119, v31
	v_max_f32_e32 v31, v119, v31
	v_cndmask_b32_e32 v118, v120, v15, vcc
	v_cndmask_b32_e32 v15, v15, v120, vcc
	v_add_f32_e32 v117, v80, v98
	v_lshl_or_b32 v118, v105, 7, v38
	v_cmp_gt_f32_e32 vcc, v117, v20
	v_min_f32_e32 v119, v117, v20
	v_max_f32_e32 v20, v117, v20
	v_cndmask_b32_e32 v120, v118, v4, vcc
	v_cndmask_b32_e32 v4, v4, v118, vcc
	v_cmp_gt_f32_e32 vcc, v119, v21
	v_min_f32_e32 v117, v119, v21
	v_max_f32_e32 v21, v119, v21
	v_cndmask_b32_e32 v118, v120, v5, vcc
	v_cndmask_b32_e32 v5, v5, v120, vcc
	v_cmp_gt_f32_e32 vcc, v117, v22
	v_min_f32_e32 v119, v117, v22
	v_max_f32_e32 v22, v117, v22
	v_cndmask_b32_e32 v120, v118, v6, vcc
	v_cndmask_b32_e32 v6, v6, v118, vcc
	v_cmp_gt_f32_e32 vcc, v119, v23
	v_min_f32_e32 v117, v119, v23
	v_max_f32_e32 v23, v119, v23
	v_cndmask_b32_e32 v118, v120, v7, vcc
	v_cndmask_b32_e32 v7, v7, v120, vcc
	v_cmp_gt_f32_e32 vcc, v117, v24
	v_min_f32_e32 v119, v117, v24
	v_max_f32_e32 v24, v117, v24
	v_cndmask_b32_e32 v120, v118, v8, vcc
	v_cndmask_b32_e32 v8, v8, v118, vcc
	v_cmp_gt_f32_e32 vcc, v119, v25
	v_min_f32_e32 v117, v119, v25
	v_max_f32_e32 v25, v119, v25
	v_cndmask_b32_e32 v118, v120, v9, vcc
	v_cndmask_b32_e32 v9, v9, v120, vcc
	v_cmp_gt_f32_e32 vcc, v117, v26
	v_min_f32_e32 v119, v117, v26
	v_max_f32_e32 v26, v117, v26
	v_cndmask_b32_e32 v120, v118, v10, vcc
	v_cndmask_b32_e32 v10, v10, v118, vcc
	v_cmp_gt_f32_e32 vcc, v119, v27
	v_min_f32_e32 v117, v119, v27
	v_max_f32_e32 v27, v119, v27
	v_cndmask_b32_e32 v118, v120, v11, vcc
	v_cndmask_b32_e32 v11, v11, v120, vcc
	v_cmp_gt_f32_e32 vcc, v117, v28
	v_min_f32_e32 v119, v117, v28
	v_max_f32_e32 v28, v117, v28
	v_cndmask_b32_e32 v120, v118, v12, vcc
	v_cndmask_b32_e32 v12, v12, v118, vcc
	v_cmp_gt_f32_e32 vcc, v119, v29
	v_min_f32_e32 v117, v119, v29
	v_max_f32_e32 v29, v119, v29
	v_cndmask_b32_e32 v118, v120, v13, vcc
	v_cndmask_b32_e32 v13, v13, v120, vcc
	v_cmp_gt_f32_e32 vcc, v117, v30
	v_min_f32_e32 v119, v117, v30
	v_max_f32_e32 v30, v117, v30
	v_cndmask_b32_e32 v120, v118, v14, vcc
	v_cndmask_b32_e32 v14, v14, v118, vcc
	v_cmp_gt_f32_e32 vcc, v119, v31
	v_min_f32_e32 v117, v119, v31
	v_max_f32_e32 v31, v119, v31
	v_cndmask_b32_e32 v118, v120, v15, vcc
	v_cndmask_b32_e32 v15, v15, v120, vcc
	v_add_f32_e32 v117, v80, v96
	v_lshl_or_b32 v118, v105, 7, v39
	v_cmp_gt_f32_e32 vcc, v117, v25
	v_min_f32_e32 v119, v117, v25
	v_max_f32_e32 v25, v117, v25
	v_cndmask_b32_e32 v120, v118, v9, vcc
	v_cndmask_b32_e32 v9, v9, v118, vcc
	v_cmp_gt_f32_e32 vcc, v119, v26
	v_min_f32_e32 v117, v119, v26
	v_max_f32_e32 v26, v119, v26
	v_cndmask_b32_e32 v118, v120, v10, vcc
	v_cndmask_b32_e32 v10, v10, v120, vcc
	v_cmp_gt_f32_e32 vcc, v117, v27
	v_min_f32_e32 v119, v117, v27
	v_max_f32_e32 v27, v117, v27
	v_cndmask_b32_e32 v120, v118, v11, vcc
	v_cndmask_b32_e32 v11, v11, v118, vcc
	v_cmp_gt_f32_e32 vcc, v119, v28
	v_min_f32_e32 v117, v119, v28
	v_max_f32_e32 v28, v119, v28
	v_cndmask_b32_e32 v118, v120, v12, vcc
	v_cndmask_b32_e32 v12, v12, v120, vcc
	v_cmp_gt_f32_e32 vcc, v117, v29
	v_min_f32_e32 v119, v117, v29
	v_max_f32_e32 v29, v117, v29
	v_cndmask_b32_e32 v120, v118, v13, vcc
	v_cndmask_b32_e32 v13, v13, v118, vcc
	v_cmp_gt_f32_e32 vcc, v119, v30
; __global__ void __launch_bounds__(NT, 2) mk_fwd(Args args) {
;     ...
;             for (int i = 0; i < 16; ++i)
; #pragma unroll
;                 for (int j = 0; j < 16; ++j) if ((i + 1) * (j + 1) <= 16) {
;                     const int m0 = T0[i] & ~127, m1 = T1[j] & ~127;
;                     const float s0 = __int_as_float(m0), s1 = __int_as_float(m1);
;                     float fv = s0 + s1; int pe = ((127 - (T0[i] & 127)) << 7) | (127 - (T1[j] & 127));
; #pragma unroll
;                     for (int u = 0; u < 16; ++u) { const bool c = fv > tv[u]; const float nv = c ? fv : tv[u]; const int ne = c ? pe : te[u]; fv = c ? tv[u] : fv; pe = c ? te[u] : pe; tv[u] = nv; te[u] = ne; }
;                 }
	v_min_f32_e32 v117, v119, v30
	v_max_f32_e32 v30, v119, v30
	v_cndmask_b32_e32 v118, v120, v14, vcc
	v_cndmask_b32_e32 v14, v14, v120, vcc
	v_cmp_gt_f32_e32 vcc, v117, v31
	v_min_f32_e32 v119, v117, v31
	v_max_f32_e32 v31, v117, v31
	v_cndmask_b32_e32 v120, v118, v15, vcc
	v_cndmask_b32_e32 v15, v15, v118, vcc
	v_add_f32_e32 v119, v80, v100
	v_lshl_or_b32 v120, v105, 7, v40
	v_cmp_gt_f32_e32 vcc, v119, v30
	v_min_f32_e32 v117, v119, v30
	v_max_f32_e32 v30, v119, v30
	v_cndmask_b32_e32 v118, v120, v14, vcc
	v_cndmask_b32_e32 v14, v14, v120, vcc
	v_cmp_gt_f32_e32 vcc, v117, v31
	v_min_f32_e32 v119, v117, v31
	v_max_f32_e32 v31, v117, v31
	v_cndmask_b32_e32 v120, v118, v15, vcc
	v_cndmask_b32_e32 v15, v15, v118, vcc
	v_add_f32_e32 v119, v79, v98
	v_lshl_or_b32 v120, v106, 7, v38
	v_cmp_gt_f32_e32 vcc, v119, v21
	v_min_f32_e32 v117, v119, v21
	v_max_f32_e32 v21, v119, v21
	v_cndmask_b32_e32 v118, v120, v5, vcc
	v_cndmask_b32_e32 v5, v5, v120, vcc
	v_cmp_gt_f32_e32 vcc, v117, v22
	v_min_f32_e32 v119, v117, v22
	v_max_f32_e32 v22, v117, v22
	v_cndmask_b32_e32 v120, v118, v6, vcc
	v_cndmask_b32_e32 v6, v6, v118, vcc
	v_cmp_gt_f32_e32 vcc, v119, v23
	v_min_f32_e32 v117, v119, v23
	v_max_f32_e32 v23, v119, v23
	v_cndmask_b32_e32 v118, v120, v7, vcc
	v_cndmask_b32_e32 v7, v7, v120, vcc
	v_cmp_gt_f32_e32 vcc, v117, v24
	v_min_f32_e32 v119, v117, v24
	v_max_f32_e32 v24, v117, v24
	v_cndmask_b32_e32 v120, v118, v8, vcc
	v_cndmask_b32_e32 v8, v8, v118, vcc
	v_cmp_gt_f32_e32 vcc, v119, v25
	v_min_f32_e32 v117, v119, v25
	v_max_f32_e32 v25, v119, v25
	v_cndmask_b32_e32 v118, v120, v9, vcc
	v_cndmask_b32_e32 v9, v9, v120, vcc
	v_cmp_gt_f32_e32 vcc, v117, v26
	v_min_f32_e32 v119, v117, v26
	v_max_f32_e32 v26, v117, v26
	v_cndmask_b32_e32 v120, v118, v10, vcc
	v_cndmask_b32_e32 v10, v10, v118, vcc
	v_cmp_gt_f32_e32 vcc, v119, v27
	v_min_f32_e32 v117, v119, v27
	v_max_f32_e32 v27, v119, v27
	v_cndmask_b32_e32 v118, v120, v11, vcc
	v_cndmask_b32_e32 v11, v11, v120, vcc
	v_cmp_gt_f32_e32 vcc, v117, v28
	v_min_f32_e32 v119, v117, v28
	v_max_f32_e32 v28, v117, v28
	v_cndmask_b32_e32 v120, v118, v12, vcc
	v_cndmask_b32_e32 v12, v12, v118, vcc
	v_cmp_gt_f32_e32 vcc, v119, v29
	v_min_f32_e32 v117, v119, v29
	v_max_f32_e32 v29, v119, v29
	v_cndmask_b32_e32 v118, v120, v13, vcc
	v_cndmask_b32_e32 v13, v13, v120, vcc
	v_cmp_gt_f32_e32 vcc, v117, v30
	v_min_f32_e32 v119, v117, v30
	v_max_f32_e32 v30, v117, v30
	v_cndmask_b32_e32 v120, v118, v14, vcc
	v_cndmask_b32_e32 v14, v14, v118, vcc
	v_cmp_gt_f32_e32 vcc, v119, v31
	v_min_f32_e32 v117, v119, v31
	v_max_f32_e32 v31, v119, v31
	v_cndmask_b32_e32 v118, v120, v15, vcc
	v_cndmask_b32_e32 v15, v15, v120, vcc
	v_add_f32_e32 v117, v79, v96
	v_lshl_or_b32 v118, v106, 7, v39
	v_cmp_gt_f32_e32 vcc, v117, v27
	v_min_f32_e32 v119, v117, v27
	v_max_f32_e32 v27, v117, v27
	v_cndmask_b32_e32 v120, v118, v11, vcc
	v_cndmask_b32_e32 v11, v11, v118, vcc
	v_cmp_gt_f32_e32 vcc, v119, v28
	v_min_f32_e32 v117, v119, v28
	v_max_f32_e32 v28, v119, v28
	v_cndmask_b32_e32 v118, v120, v12, vcc
	v_cndmask_b32_e32 v12, v12, v120, vcc
	v_cmp_gt_f32_e32 vcc, v117, v29
	v_min_f32_e32 v119, v117, v29
	v_max_f32_e32 v29, v117, v29
	v_cndmask_b32_e32 v120, v118, v13, vcc
	v_cndmask_b32_e32 v13, v13, v118, vcc
	v_cmp_gt_f32_e32 vcc, v119, v30
	v_min_f32_e32 v117, v119, v30
	v_max_f32_e32 v30, v119, v30
	v_cndmask_b32_e32 v118, v120, v14, vcc
	v_cndmask_b32_e32 v14, v14, v120, vcc
	v_cmp_gt_f32_e32 vcc, v117, v31
	v_min_f32_e32 v119, v117, v31
	v_max_f32_e32 v31, v117, v31
	v_cndmask_b32_e32 v120, v118, v15, vcc
	v_cndmask_b32_e32 v15, v15, v118, vcc
	v_add_f32_e32 v119, v78, v98
	v_lshl_or_b32 v120, v107, 7, v38
	v_cmp_gt_f32_e32 vcc, v119, v22
	v_min_f32_e32 v117, v119, v22
	v_max_f32_e32 v22, v119, v22
	v_cndmask_b32_e32 v118, v120, v6, vcc
	v_cndmask_b32_e32 v6, v6, v120, vcc
	v_cmp_gt_f32_e32 vcc, v117, v23
	v_min_f32_e32 v119, v117, v23
	v_max_f32_e32 v23, v117, v23
	v_cndmask_b32_e32 v120, v118, v7, vcc
	v_cndmask_b32_e32 v7, v7, v118, vcc
	v_cmp_gt_f32_e32 vcc, v119, v24
	v_min_f32_e32 v117, v119, v24
	v_max_f32_e32 v24, v119, v24
	v_cndmask_b32_e32 v118, v120, v8, vcc
	v_cndmask_b32_e32 v8, v8, v120, vcc
	v_cmp_gt_f32_e32 vcc, v117, v25
	v_min_f32_e32 v119, v117, v25
	v_max_f32_e32 v25, v117, v25
	v_cndmask_b32_e32 v120, v118, v9, vcc
	v_cndmask_b32_e32 v9, v9, v118, vcc
	v_cmp_gt_f32_e32 vcc, v119, v26
	v_min_f32_e32 v117, v119, v26
	v_max_f32_e32 v26, v119, v26
	v_cndmask_b32_e32 v118, v120, v10, vcc
	v_cndmask_b32_e32 v10, v10, v120, vcc
	v_cmp_gt_f32_e32 vcc, v117, v27
	v_min_f32_e32 v119, v117, v27
	v_max_f32_e32 v27, v117, v27
	v_cndmask_b32_e32 v120, v118, v11, vcc
	v_cndmask_b32_e32 v11, v11, v118, vcc
	v_cmp_gt_f32_e32 vcc, v119, v28
	v_min_f32_e32 v117, v119, v28
	v_max_f32_e32 v28, v119, v28
	v_cndmask_b32_e32 v118, v120, v12, vcc
	v_cndmask_b32_e32 v12, v12, v120, vcc
	v_cmp_gt_f32_e32 vcc, v117, v29
	v_min_f32_e32 v119, v117, v29
	v_max_f32_e32 v29, v117, v29
	v_cndmask_b32_e32 v120, v118, v13, vcc
	v_cndmask_b32_e32 v13, v13, v118, vcc
	v_cmp_gt_f32_e32 vcc, v119, v30
	v_min_f32_e32 v117, v119, v30
	v_max_f32_e32 v30, v119, v30
	v_cndmask_b32_e32 v118, v120, v14, vcc
	v_cndmask_b32_e32 v14, v14, v120, vcc
	v_cmp_gt_f32_e32 vcc, v117, v31
	v_min_f32_e32 v119, v117, v31
	v_max_f32_e32 v31, v117, v31
	v_cndmask_b32_e32 v120, v118, v15, vcc
	v_cndmask_b32_e32 v15, v15, v118, vcc
	v_add_f32_e32 v119, v78, v96
	v_lshl_or_b32 v120, v107, 7, v39
	v_cmp_gt_f32_e32 vcc, v119, v29
	v_min_f32_e32 v117, v119, v29
	v_max_f32_e32 v29, v119, v29
	v_cndmask_b32_e32 v118, v120, v13, vcc
	v_cndmask_b32_e32 v13, v13, v120, vcc
; __global__ void __launch_bounds__(NT, 2) mk_fwd(Args args) {
;     ...
;             for (int i = 0; i < 16; ++i)
; #pragma unroll
;                 for (int j = 0; j < 16; ++j) if ((i + 1) * (j + 1) <= 16) {
;                     const int m0 = T0[i] & ~127, m1 = T1[j] & ~127;
;                     const float s0 = __int_as_float(m0), s1 = __int_as_float(m1);
;                     float fv = s0 + s1; int pe = ((127 - (T0[i] & 127)) << 7) | (127 - (T1[j] & 127));
; #pragma unroll
;                     for (int u = 0; u < 16; ++u) { const bool c = fv > tv[u]; const float nv = c ? fv : tv[u]; const int ne = c ? pe : te[u]; fv = c ? tv[u] : fv; pe = c ? te[u] : pe; tv[u] = nv; te[u] = ne; }
;                 }
	v_cmp_gt_f32_e32 vcc, v117, v30
	v_min_f32_e32 v119, v117, v30
	v_max_f32_e32 v30, v117, v30
	v_cndmask_b32_e32 v120, v118, v14, vcc
	v_cndmask_b32_e32 v14, v14, v118, vcc
	v_cmp_gt_f32_e32 vcc, v119, v31
	v_min_f32_e32 v117, v119, v31
	v_max_f32_e32 v31, v119, v31
	v_cndmask_b32_e32 v118, v120, v15, vcc
	v_cndmask_b32_e32 v15, v15, v120, vcc
	v_add_f32_e32 v117, v77, v98
	v_lshl_or_b32 v118, v108, 7, v38
	v_cmp_gt_f32_e32 vcc, v117, v23
	v_min_f32_e32 v119, v117, v23
	v_max_f32_e32 v23, v117, v23
	v_cndmask_b32_e32 v120, v118, v7, vcc
	v_cndmask_b32_e32 v7, v7, v118, vcc
	v_cmp_gt_f32_e32 vcc, v119, v24
	v_min_f32_e32 v117, v119, v24
	v_max_f32_e32 v24, v119, v24
	v_cndmask_b32_e32 v118, v120, v8, vcc
	v_cndmask_b32_e32 v8, v8, v120, vcc
	v_cmp_gt_f32_e32 vcc, v117, v25
	v_min_f32_e32 v119, v117, v25
	v_max_f32_e32 v25, v117, v25
	v_cndmask_b32_e32 v120, v118, v9, vcc
	v_cndmask_b32_e32 v9, v9, v118, vcc
	v_cmp_gt_f32_e32 vcc, v119, v26
	v_min_f32_e32 v117, v119, v26
	v_max_f32_e32 v26, v119, v26
	v_cndmask_b32_e32 v118, v120, v10, vcc
	v_cndmask_b32_e32 v10, v10, v120, vcc
	v_cmp_gt_f32_e32 vcc, v117, v27
	v_min_f32_e32 v119, v117, v27
	v_max_f32_e32 v27, v117, v27
	v_cndmask_b32_e32 v120, v118, v11, vcc
	v_cndmask_b32_e32 v11, v11, v118, vcc
	v_cmp_gt_f32_e32 vcc, v119, v28
	v_min_f32_e32 v117, v119, v28
	v_max_f32_e32 v28, v119, v28
	v_cndmask_b32_e32 v118, v120, v12, vcc
	v_cndmask_b32_e32 v12, v12, v120, vcc
	v_cmp_gt_f32_e32 vcc, v117, v29
	v_min_f32_e32 v119, v117, v29
	v_max_f32_e32 v29, v117, v29
	v_cndmask_b32_e32 v120, v118, v13, vcc
	v_cndmask_b32_e32 v13, v13, v118, vcc
	v_cmp_gt_f32_e32 vcc, v119, v30
	v_min_f32_e32 v117, v119, v30
	v_max_f32_e32 v30, v119, v30
	v_cndmask_b32_e32 v118, v120, v14, vcc
	v_cndmask_b32_e32 v14, v14, v120, vcc
	v_cmp_gt_f32_e32 vcc, v117, v31
	v_min_f32_e32 v119, v117, v31
	v_max_f32_e32 v31, v117, v31
	v_cndmask_b32_e32 v120, v118, v15, vcc
	v_cndmask_b32_e32 v15, v15, v118, vcc
	v_add_f32_e32 v119, v77, v96
	v_lshl_or_b32 v120, v108, 7, v39
	v_cmp_gt_f32_e32 vcc, v119, v31
	v_min_f32_e32 v117, v119, v31
	v_max_f32_e32 v31, v119, v31
	v_cndmask_b32_e32 v118, v120, v15, vcc
	v_cndmask_b32_e32 v15, v15, v120, vcc
	v_add_f32_e32 v117, v76, v98
	v_lshl_or_b32 v118, v109, 7, v38
	v_cmp_gt_f32_e32 vcc, v117, v24
	v_min_f32_e32 v119, v117, v24
	v_max_f32_e32 v24, v117, v24
	v_cndmask_b32_e32 v120, v118, v8, vcc
	v_cndmask_b32_e32 v8, v8, v118, vcc
	v_cmp_gt_f32_e32 vcc, v119, v25
	v_min_f32_e32 v117, v119, v25
	v_max_f32_e32 v25, v119, v25
	v_cndmask_b32_e32 v118, v120, v9, vcc
	v_cndmask_b32_e32 v9, v9, v120, vcc
	v_cmp_gt_f32_e32 vcc, v117, v26
	v_min_f32_e32 v119, v117, v26
	v_max_f32_e32 v26, v117, v26
	v_cndmask_b32_e32 v120, v118, v10, vcc
	v_cndmask_b32_e32 v10, v10, v118, vcc
	v_cmp_gt_f32_e32 vcc, v119, v27
	v_min_f32_e32 v117, v119, v27
	v_max_f32_e32 v27, v119, v27
	v_cndmask_b32_e32 v118, v120, v11, vcc
	v_cndmask_b32_e32 v11, v11, v120, vcc
	v_cmp_gt_f32_e32 vcc, v117, v28
	v_min_f32_e32 v119, v117, v28
	v_max_f32_e32 v28, v117, v28
	v_cndmask_b32_e32 v120, v118, v12, vcc
	v_cndmask_b32_e32 v12, v12, v118, vcc
	v_cmp_gt_f32_e32 vcc, v119, v29
	v_min_f32_e32 v117, v119, v29
	v_max_f32_e32 v29, v119, v29
	v_cndmask_b32_e32 v118, v120, v13, vcc
	v_cndmask_b32_e32 v13, v13, v120, vcc
	v_cmp_gt_f32_e32 vcc, v117, v30
	v_min_f32_e32 v119, v117, v30
	v_max_f32_e32 v30, v117, v30
	v_cndmask_b32_e32 v120, v118, v14, vcc
	v_cndmask_b32_e32 v14, v14, v118, vcc
	v_cmp_gt_f32_e32 vcc, v119, v31
	v_min_f32_e32 v117, v119, v31
	v_max_f32_e32 v31, v119, v31
	v_cndmask_b32_e32 v118, v120, v15, vcc
	v_cndmask_b32_e32 v15, v15, v120, vcc
	v_add_f32_e32 v117, v75, v98
	v_lshl_or_b32 v118, v110, 7, v38
	v_cmp_gt_f32_e32 vcc, v117, v25
	v_min_f32_e32 v119, v117, v25
	v_max_f32_e32 v25, v117, v25
	v_cndmask_b32_e32 v120, v118, v9, vcc
	v_cndmask_b32_e32 v9, v9, v118, vcc
	v_cmp_gt_f32_e32 vcc, v119, v26
	v_min_f32_e32 v117, v119, v26
	v_max_f32_e32 v26, v119, v26
	v_cndmask_b32_e32 v118, v120, v10, vcc
	v_cndmask_b32_e32 v10, v10, v120, vcc
	v_cmp_gt_f32_e32 vcc, v117, v27
	v_min_f32_e32 v119, v117, v27
	v_max_f32_e32 v27, v117, v27
	v_cndmask_b32_e32 v120, v118, v11, vcc
	v_cndmask_b32_e32 v11, v11, v118, vcc
	v_cmp_gt_f32_e32 vcc, v119, v28
	v_min_f32_e32 v117, v119, v28
	v_max_f32_e32 v28, v119, v28
	v_cndmask_b32_e32 v118, v120, v12, vcc
	v_cndmask_b32_e32 v12, v12, v120, vcc
	v_cmp_gt_f32_e32 vcc, v117, v29
	v_min_f32_e32 v119, v117, v29
	v_max_f32_e32 v29, v117, v29
	v_cndmask_b32_e32 v120, v118, v13, vcc
	v_cndmask_b32_e32 v13, v13, v118, vcc
	v_cmp_gt_f32_e32 vcc, v119, v30
	v_min_f32_e32 v117, v119, v30
	v_max_f32_e32 v30, v119, v30
	v_cndmask_b32_e32 v118, v120, v14, vcc
	v_cndmask_b32_e32 v14, v14, v120, vcc
	v_cmp_gt_f32_e32 vcc, v117, v31
	v_min_f32_e32 v119, v117, v31
	v_max_f32_e32 v31, v117, v31
	v_cndmask_b32_e32 v120, v118, v15, vcc
	v_cndmask_b32_e32 v15, v15, v118, vcc
	v_add_f32_e32 v119, v74, v98
	v_lshl_or_b32 v120, v111, 7, v38
	v_cmp_gt_f32_e32 vcc, v119, v26
	v_min_f32_e32 v117, v119, v26
	v_max_f32_e32 v26, v119, v26
	v_cndmask_b32_e32 v118, v120, v10, vcc
	v_cndmask_b32_e32 v10, v10, v120, vcc
	v_cmp_gt_f32_e32 vcc, v117, v27
	v_min_f32_e32 v119, v117, v27
	v_max_f32_e32 v27, v117, v27
	v_cndmask_b32_e32 v120, v118, v11, vcc
	v_cndmask_b32_e32 v11, v11, v118, vcc
	v_cmp_gt_f32_e32 vcc, v119, v28
	v_min_f32_e32 v117, v119, v28
	v_max_f32_e32 v28, v119, v28
	v_cndmask_b32_e32 v118, v120, v12, vcc
	v_cndmask_b32_e32 v12, v12, v120, vcc
	v_cmp_gt_f32_e32 vcc, v117, v29
	v_min_f32_e32 v119, v117, v29
	v_max_f32_e32 v29, v117, v29
	v_cndmask_b32_e32 v120, v118, v13, vcc
; __global__ void __launch_bounds__(NT, 2) mk_fwd(Args args) {
;     ...
;                     for (int u = 0; u < 16; ++u) { const bool c = fv > tv[u]; const float nv = c ? fv : tv[u]; const int ne = c ? pe : te[u]; fv = c ? tv[u] : fv; pe = c ? te[u] : pe; tv[u] = nv; te[u] = ne; }
;                 }
;             {
;                 const float mx = tv[0]; float sum = 0.f;
; #pragma unroll
;                 for (int j = 0; j < 16; ++j) { tv[j] = __expf(tv[j] - mx); sum += tv[j]; }
;                 const float inv = 1.0f / sum;
; #pragma unroll
;                 for (int j = 0; j < 16; ++j) tv[j] *= inv;
;             }
;             const size_t o = (size_t)(tt * 64 + lane) * 128 + h * 16;
; #pragma unroll
;             for (int j = 0; j < 16; ++j) { EIDX[o + j] = te[j]; GATE[o + j] = tv[j]; }
	v_cndmask_b32_e32 v13, v13, v118, vcc
	v_cmp_gt_f32_e32 vcc, v119, v30
	v_min_f32_e32 v117, v119, v30
	v_max_f32_e32 v30, v119, v30
	v_cndmask_b32_e32 v118, v120, v14, vcc
	v_cndmask_b32_e32 v14, v14, v120, vcc
	v_cmp_gt_f32_e32 vcc, v117, v31
	v_min_f32_e32 v119, v117, v31
	v_max_f32_e32 v31, v117, v31
	v_cndmask_b32_e32 v120, v118, v15, vcc
	v_cndmask_b32_e32 v15, v15, v118, vcc
	v_add_f32_e32 v119, v73, v98
	v_lshl_or_b32 v120, v112, 7, v38
	v_cmp_gt_f32_e32 vcc, v119, v27
	v_min_f32_e32 v117, v119, v27
	v_max_f32_e32 v27, v119, v27
	v_cndmask_b32_e32 v118, v120, v11, vcc
	v_cndmask_b32_e32 v11, v11, v120, vcc
	v_cmp_gt_f32_e32 vcc, v117, v28
	v_min_f32_e32 v119, v117, v28
	v_max_f32_e32 v28, v117, v28
	v_cndmask_b32_e32 v120, v118, v12, vcc
	v_cndmask_b32_e32 v12, v12, v118, vcc
	v_cmp_gt_f32_e32 vcc, v119, v29
	v_min_f32_e32 v117, v119, v29
	v_max_f32_e32 v29, v119, v29
	v_cndmask_b32_e32 v118, v120, v13, vcc
	v_cndmask_b32_e32 v13, v13, v120, vcc
	v_cmp_gt_f32_e32 vcc, v117, v30
	v_min_f32_e32 v119, v117, v30
	v_max_f32_e32 v30, v117, v30
	v_cndmask_b32_e32 v120, v118, v14, vcc
	v_cndmask_b32_e32 v14, v14, v118, vcc
	v_cmp_gt_f32_e32 vcc, v119, v31
	v_min_f32_e32 v117, v119, v31
	v_max_f32_e32 v31, v119, v31
	v_cndmask_b32_e32 v118, v120, v15, vcc
	v_cndmask_b32_e32 v15, v15, v120, vcc
	v_add_f32_e32 v117, v72, v98
	v_lshl_or_b32 v118, v113, 7, v38
	v_cmp_gt_f32_e32 vcc, v117, v28
	v_min_f32_e32 v119, v117, v28
	v_max_f32_e32 v28, v117, v28
	v_cndmask_b32_e32 v120, v118, v12, vcc
	v_cndmask_b32_e32 v12, v12, v118, vcc
	v_cmp_gt_f32_e32 vcc, v119, v29
	v_min_f32_e32 v117, v119, v29
	v_max_f32_e32 v29, v119, v29
	v_cndmask_b32_e32 v118, v120, v13, vcc
	v_cndmask_b32_e32 v13, v13, v120, vcc
	v_cmp_gt_f32_e32 vcc, v117, v30
	v_min_f32_e32 v119, v117, v30
	v_max_f32_e32 v30, v117, v30
	v_cndmask_b32_e32 v120, v118, v14, vcc
	v_cndmask_b32_e32 v14, v14, v118, vcc
	v_cmp_gt_f32_e32 vcc, v119, v31
	v_min_f32_e32 v117, v119, v31
	v_max_f32_e32 v31, v119, v31
	v_cndmask_b32_e32 v118, v120, v15, vcc
	v_cndmask_b32_e32 v15, v15, v120, vcc
	v_add_f32_e32 v117, v71, v98
	v_lshl_or_b32 v118, v114, 7, v38
	v_cmp_gt_f32_e32 vcc, v117, v29
	v_min_f32_e32 v119, v117, v29
	v_max_f32_e32 v29, v117, v29
	v_cndmask_b32_e32 v120, v118, v13, vcc
	v_cndmask_b32_e32 v13, v13, v118, vcc
	v_cmp_gt_f32_e32 vcc, v119, v30
	v_min_f32_e32 v117, v119, v30
	v_max_f32_e32 v30, v119, v30
	v_cndmask_b32_e32 v118, v120, v14, vcc
	v_cndmask_b32_e32 v14, v14, v120, vcc
	v_cmp_gt_f32_e32 vcc, v117, v31
	v_min_f32_e32 v119, v117, v31
	v_max_f32_e32 v31, v117, v31
	v_cndmask_b32_e32 v120, v118, v15, vcc
	v_cndmask_b32_e32 v15, v15, v118, vcc
	v_add_f32_e32 v119, v70, v98
	v_lshl_or_b32 v120, v115, 7, v38
	v_cmp_gt_f32_e32 vcc, v119, v30
	v_min_f32_e32 v117, v119, v30
	v_max_f32_e32 v30, v119, v30
	v_cndmask_b32_e32 v118, v120, v14, vcc
	v_cndmask_b32_e32 v14, v14, v120, vcc
	v_cmp_gt_f32_e32 vcc, v117, v31
	v_min_f32_e32 v119, v117, v31
	v_max_f32_e32 v31, v117, v31
	v_cndmask_b32_e32 v120, v118, v15, vcc
	v_cndmask_b32_e32 v15, v15, v118, vcc
	v_add_f32_e32 v119, v69, v98
	v_lshl_or_b32 v120, v116, 7, v38
	v_cmp_gt_f32_e32 vcc, v119, v31
	v_min_f32_e32 v117, v119, v31
	v_max_f32_e32 v31, v119, v31
	v_cndmask_b32_e32 v118, v120, v15, vcc
	v_cndmask_b32_e32 v15, v15, v120, vcc
	v_sub_f32_e32 v54, v16, v16
	v_sub_f32_e32 v17, v17, v16
	v_sub_f32_e32 v18, v18, v16
	v_sub_f32_e32 v19, v19, v16
	v_sub_f32_e32 v20, v20, v16
	v_sub_f32_e32 v21, v21, v16
	v_sub_f32_e32 v22, v22, v16
	v_sub_f32_e32 v23, v23, v16
	v_sub_f32_e32 v24, v24, v16
	v_sub_f32_e32 v25, v25, v16
	v_sub_f32_e32 v26, v26, v16
	v_sub_f32_e32 v27, v27, v16
	v_sub_f32_e32 v28, v28, v16
	v_sub_f32_e32 v29, v29, v16
	v_sub_f32_e32 v30, v30, v16
	v_sub_f32_e32 v31, v31, v16
	v_mul_f32_e32 v16, 0x3fb8aa3b, v54
	v_mul_f32_e32 v17, 0x3fb8aa3b, v17
	v_mul_f32_e32 v18, 0x3fb8aa3b, v18
	v_mul_f32_e32 v19, 0x3fb8aa3b, v19
	v_mul_f32_e32 v20, 0x3fb8aa3b, v20
	v_mul_f32_e32 v21, 0x3fb8aa3b, v21
	v_mul_f32_e32 v22, 0x3fb8aa3b, v22
	v_mul_f32_e32 v23, 0x3fb8aa3b, v23
	v_mul_f32_e32 v24, 0x3fb8aa3b, v24
	v_mul_f32_e32 v25, 0x3fb8aa3b, v25
	v_mul_f32_e32 v26, 0x3fb8aa3b, v26
	v_mul_f32_e32 v27, 0x3fb8aa3b, v27
	v_mul_f32_e32 v28, 0x3fb8aa3b, v28
	v_mul_f32_e32 v29, 0x3fb8aa3b, v29
	v_mul_f32_e32 v30, 0x3fb8aa3b, v30
	v_mul_f32_e32 v31, 0x3fb8aa3b, v31
	v_exp_f32_e32 v16, v16
	v_exp_f32_e32 v17, v17
	v_exp_f32_e32 v18, v18
	v_exp_f32_e32 v19, v19
	v_exp_f32_e32 v20, v20
	v_exp_f32_e32 v21, v21
	v_exp_f32_e32 v22, v22
	v_exp_f32_e32 v23, v23
	v_exp_f32_e32 v24, v24
	v_exp_f32_e32 v25, v25
	v_exp_f32_e32 v26, v26
	v_exp_f32_e32 v27, v27
	v_exp_f32_e32 v28, v28
	v_exp_f32_e32 v29, v29
	v_exp_f32_e32 v30, v30
	v_exp_f32_e32 v31, v31
	s_nop 0
	v_add_f32_e32 v121, 0, v16
	v_add_f32_e32 v121, v121, v17
	v_add_f32_e32 v121, v121, v18
	v_add_f32_e32 v121, v121, v19
	v_add_f32_e32 v121, v121, v20
	v_add_f32_e32 v121, v121, v21
	v_add_f32_e32 v121, v121, v22
	v_add_f32_e32 v121, v121, v23
	v_add_f32_e32 v121, v121, v24
	v_add_f32_e32 v121, v121, v25
	v_add_f32_e32 v121, v121, v26
	v_add_f32_e32 v121, v121, v27
	v_add_f32_e32 v121, v121, v28
	v_add_f32_e32 v121, v121, v29
	v_add_f32_e32 v121, v121, v30
	v_add_f32_e32 v121, v121, v31
	v_div_scale_f32 v122, s[2:3], v121, v121, 1.0
	v_rcp_f32_e32 v123, v122
	v_readlane_b32 s0, v249, 8
	v_fma_f32 v124, -v122, v123, 1.0
	v_fmac_f32_e32 v123, v124, v123
	v_div_scale_f32 v124, vcc, 1.0, v121, 1.0
	v_mul_f32_e32 v125, v124, v123
	v_fma_f32 v126, -v122, v125, v124
	v_fmac_f32_e32 v125, v126, v123
	v_fma_f32 v122, -v122, v125, v124
	v_div_fmas_f32 v122, v122, v123, v125
	v_div_fixup_f32 v121, v122, v121, 1.0
	v_lshl_or_b32 v54, s0, 15, v61
	v_readlane_b32 s46, v249, 31
	v_readlane_b32 s47, v249, 32
	v_readlane_b32 s48, v249, 42
	v_readlane_b32 s49, v249, 43
	v_readlane_b32 s1, v249, 25
	v_mul_f32_e32 v16, v121, v16
	v_mul_f32_e32 v17, v121, v17
	v_mul_f32_e32 v18, v121, v18
	v_mul_f32_e32 v19, v121, v19
	v_mul_f32_e32 v20, v121, v20
	v_mul_f32_e32 v21, v121, v21
	v_mul_f32_e32 v22, v121, v22
	v_mul_f32_e32 v23, v121, v23
	v_mul_f32_e32 v24, v121, v24
	v_mul_f32_e32 v25, v121, v25
	v_mul_f32_e32 v26, v121, v26
	v_mul_f32_e32 v27, v121, v27
	v_mul_f32_e32 v28, v121, v28
	v_mul_f32_e32 v29, v121, v29
	v_mul_f32_e32 v30, v121, v30
	v_mul_f32_e32 v31, v121, v31
	global_store_dwordx4 v54, v[0:3], s[46:47]
	global_store_dwordx4 v54, v[16:19], s[48:49]
	global_store_dwordx4 v54, v[4:7], s[46:47] offset:16
	global_store_dwordx4 v54, v[20:23], s[48:49] offset:16
	global_store_dwordx4 v54, v[8:11], s[46:47] offset:32
	global_store_dwordx4 v54, v[24:27], s[48:49] offset:32
	global_store_dwordx4 v54, v[12:15], s[46:47] offset:48
	global_store_dwordx4 v54, v[28:31], s[48:49] offset:48
	s_add_i32 s97, s97, s1
	s_cmpk_gt_i32 s97, 0x7ff
	s_cbranch_scc0 .LBB0_815
